# Resid epilogues: row sum-of-squares cross-lane steps (xor 16 / xor 32) via v_permlane16_swap / v_permlane32_swap instead of ds_bpermute
# speedup vs baseline: 1.0057x; 1.0005x over previous
.LBB0_690:
	s_add_u32 s0, s58, s85
	s_addc_u32 s3, s59, s84
	s_add_u32 s58, s0, 0x310000
	s_addc_u32 s59, s3, 0
	s_and_b64 vcc, exec, s[6:7]
	s_cbranch_vccnz .LBB0_694
	v_cmp_lt_i32_e32 vcc, v227, v222
	s_nop 1
	v_cndmask_b32_e32 v146, v221, v227, vcc
	v_lshlrev_b32_e32 v146, 2, v146
	v_mov_b32_e32 v146, v166
	s_nop 1
	v_permlane16_swap_b32_e32 v146, v166
	v_cmp_lt_i32_e32 vcc, v228, v222
	s_waitcnt lgkmcnt(0)
	v_add_f32_e32 v146, v166, v146
	v_cndmask_b32_e32 v147, v221, v228, vcc
	v_lshlrev_b32_e32 v147, 2, v147
	v_mov_b32_e32 v147, v146
	s_nop 1
	v_permlane32_swap_b32_e32 v147, v146
	s_waitcnt lgkmcnt(0)
	v_add_f32_e32 v244, v146, v147

.LBB0_703:
	v_cmp_lt_i32_e32 vcc, v227, v222
	s_nop 1
	v_cndmask_b32_e32 v130, v221, v227, vcc
	v_lshlrev_b32_e32 v130, 2, v130
	v_mov_b32_e32 v130, v138
	s_nop 1
	v_permlane16_swap_b32_e32 v130, v138
	v_cmp_lt_i32_e32 vcc, v228, v222
	s_waitcnt lgkmcnt(0)
	v_add_f32_e32 v130, v138, v130
	v_cndmask_b32_e32 v131, v221, v228, vcc
	v_lshlrev_b32_e32 v131, 2, v131
	v_mov_b32_e32 v131, v130
	s_nop 1
	v_permlane32_swap_b32_e32 v131, v130
	s_waitcnt lgkmcnt(0)
	v_add_f32_e32 v245, v130, v131

.LBB0_715:
	v_cmp_lt_i32_e32 vcc, v227, v222
	s_nop 1
	v_cndmask_b32_e32 v114, v221, v227, vcc
	v_lshlrev_b32_e32 v114, 2, v114
	v_mov_b32_e32 v114, v122
	s_nop 1
	v_permlane16_swap_b32_e32 v114, v122
	v_cmp_lt_i32_e32 vcc, v228, v222
	s_waitcnt lgkmcnt(0)
	v_add_f32_e32 v114, v122, v114
	v_cndmask_b32_e32 v115, v221, v228, vcc
	v_lshlrev_b32_e32 v115, 2, v115
	v_mov_b32_e32 v115, v114
	s_nop 1
	v_permlane32_swap_b32_e32 v115, v114
	s_waitcnt lgkmcnt(0)
	v_add_f32_e32 v246, v114, v115

.LBB0_727:
	v_cmp_lt_i32_e32 vcc, v227, v222
	s_nop 1
	v_cndmask_b32_e32 v98, v221, v227, vcc
	v_lshlrev_b32_e32 v98, 2, v98
	v_mov_b32_e32 v98, v106
	s_nop 1
	v_permlane16_swap_b32_e32 v98, v106
	v_cmp_lt_i32_e32 vcc, v228, v222
	s_waitcnt lgkmcnt(0)
	v_add_f32_e32 v98, v106, v98
	v_cndmask_b32_e32 v99, v221, v228, vcc
	v_lshlrev_b32_e32 v99, 2, v99
	v_mov_b32_e32 v99, v98
	s_nop 1
	v_permlane32_swap_b32_e32 v99, v98
	s_waitcnt lgkmcnt(0)
	v_add_f32_e32 v247, v98, v99

.LBB0_739:
	v_cmp_lt_i32_e32 vcc, v227, v222
	s_nop 1
	v_cndmask_b32_e32 v50, v221, v227, vcc
	v_lshlrev_b32_e32 v50, 2, v50
	v_mov_b32_e32 v50, v74
	s_nop 1
	v_permlane16_swap_b32_e32 v50, v74
	v_cmp_lt_i32_e32 vcc, v228, v222
	s_waitcnt lgkmcnt(0)
	v_add_f32_e32 v50, v74, v50
	v_cndmask_b32_e32 v51, v221, v228, vcc
	v_lshlrev_b32_e32 v51, 2, v51
	v_mov_b32_e32 v51, v50
	s_nop 1
	v_permlane32_swap_b32_e32 v51, v50
	s_waitcnt lgkmcnt(0)
	v_add_f32_e32 v248, v50, v51

.LBB0_751:
	v_cmp_lt_i32_e32 vcc, v227, v222
	s_nop 1
	v_cndmask_b32_e32 v34, v221, v227, vcc
	v_lshlrev_b32_e32 v34, 2, v34
	v_mov_b32_e32 v34, v42
	s_nop 1
	v_permlane16_swap_b32_e32 v34, v42
	v_cmp_lt_i32_e32 vcc, v228, v222
	s_waitcnt lgkmcnt(0)
	v_add_f32_e32 v34, v42, v34
	v_cndmask_b32_e32 v35, v221, v228, vcc
	v_lshlrev_b32_e32 v35, 2, v35
	v_mov_b32_e32 v35, v34
	s_nop 1
	v_permlane32_swap_b32_e32 v35, v34
	s_waitcnt lgkmcnt(0)
	v_add_f32_e32 v249, v34, v35

.LBB0_763:
	v_cmp_lt_i32_e32 vcc, v227, v222
	s_nop 1
	v_cndmask_b32_e32 v18, v221, v227, vcc
	v_lshlrev_b32_e32 v18, 2, v18
	v_mov_b32_e32 v18, v26
	s_nop 1
	v_permlane16_swap_b32_e32 v18, v26
	v_cmp_lt_i32_e32 vcc, v228, v222
	s_waitcnt lgkmcnt(0)
	v_add_f32_e32 v18, v26, v18
	v_cndmask_b32_e32 v19, v221, v228, vcc
	v_lshlrev_b32_e32 v19, 2, v19
	v_mov_b32_e32 v19, v18
	s_nop 1
	v_permlane32_swap_b32_e32 v19, v18
	s_waitcnt lgkmcnt(0)
	v_add_f32_e32 v250, v18, v19

.LBB0_773:
	v_cmp_lt_i32_e32 vcc, v227, v222
	s_nop 1
	v_cndmask_b32_e32 v2, v221, v227, vcc
	v_lshlrev_b32_e32 v2, 2, v2
	v_mov_b32_e32 v2, v10
	s_nop 1
	v_permlane16_swap_b32_e32 v2, v10
	v_cmp_lt_i32_e32 vcc, v228, v222
	s_waitcnt lgkmcnt(0)
	v_add_f32_e32 v2, v10, v2
	v_cndmask_b32_e32 v3, v221, v228, vcc
	v_lshlrev_b32_e32 v3, 2, v3
	v_mov_b32_e32 v3, v2
	s_nop 1
	v_permlane32_swap_b32_e32 v3, v2
	s_and_saveexec_b64 s[6:7], s[8:9]
	s_cbranch_execz .LBB0_775
	v_lshl_add_u64 v[4:5], v[200:201], 2, s[58:59]
	s_waitcnt lgkmcnt(0)
	v_add_f32_e32 v2, v2, v3
	global_atomic_add_f32 v[4:5], v244, off
	global_atomic_add_f32 v[4:5], v245, off offset:64
	global_atomic_add_f32 v[4:5], v246, off offset:128
	global_atomic_add_f32 v[4:5], v247, off offset:192
	global_atomic_add_f32 v[4:5], v248, off offset:512
	global_atomic_add_f32 v[4:5], v249, off offset:576
	global_atomic_add_f32 v[4:5], v250, off offset:640
	global_atomic_add_f32 v[4:5], v2, off offset:704

.LBB0_806:
	s_mul_hi_u32 s0, s1, 0x18000
	s_mul_i32 s1, s1, 0x18000
	s_add_u32 s1, s4, s1
	s_addc_u32 s0, s5, s0
	s_add_u32 s10, s1, 0x310000
	s_addc_u32 s11, s0, 0
	s_and_b64 vcc, exec, s[6:7]
	v_cmp_eq_u32_e64 s[4:5], 0, v1
	s_cbranch_vccnz .LBB0_810
	v_cmp_lt_i32_e32 vcc, v227, v222
	s_nop 1
	v_cndmask_b32_e32 v1, v221, v227, vcc
	v_lshlrev_b32_e32 v1, 2, v1
	v_mov_b32_e32 v1, v102
	s_nop 1
	v_permlane16_swap_b32_e32 v1, v102
	v_cmp_lt_i32_e32 vcc, v228, v222
	s_waitcnt lgkmcnt(0)
	v_add_f32_e32 v1, v102, v1
	v_cndmask_b32_e32 v82, v221, v228, vcc
	v_lshlrev_b32_e32 v82, 2, v82
	v_mov_b32_e32 v82, v1
	s_nop 1
	v_permlane32_swap_b32_e32 v82, v1
	s_and_saveexec_b64 s[12:13], s[4:5]
	s_cbranch_execz .LBB0_809
	v_lshl_add_u64 v[84:85], v[120:121], 2, s[10:11]
	s_waitcnt lgkmcnt(0)
	v_add_f32_e32 v1, v1, v82
	global_atomic_add_f32 v[84:85], v1, off

.LBB0_819:
	v_cmp_lt_i32_e32 vcc, v227, v222
	s_nop 1
	v_cndmask_b32_e32 v1, v221, v227, vcc
	v_lshlrev_b32_e32 v1, 2, v1
	v_mov_b32_e32 v1, v70
	s_nop 1
	v_permlane16_swap_b32_e32 v1, v70
	v_cmp_lt_i32_e32 vcc, v228, v222
	s_waitcnt lgkmcnt(0)
	v_add_f32_e32 v1, v70, v1
	v_cndmask_b32_e32 v42, v221, v228, vcc
	v_lshlrev_b32_e32 v42, 2, v42
	v_mov_b32_e32 v42, v1
	s_nop 1
	v_permlane32_swap_b32_e32 v42, v1
	s_and_saveexec_b64 s[12:13], s[4:5]
	s_cbranch_execz .LBB0_821
	v_lshl_add_u64 v[44:45], v[120:121], 2, s[10:11]
	s_waitcnt lgkmcnt(0)
	v_add_f32_e32 v1, v1, v42
	global_atomic_add_f32 v[44:45], v1, off offset:64

.LBB0_831:
	v_cmp_lt_i32_e32 vcc, v227, v222
	s_nop 1
	v_cndmask_b32_e32 v1, v221, v227, vcc
	v_lshlrev_b32_e32 v1, 2, v1
	v_mov_b32_e32 v1, v26
	s_nop 1
	v_permlane16_swap_b32_e32 v1, v26
	v_cmp_lt_i32_e32 vcc, v228, v222
	s_waitcnt lgkmcnt(0)
	v_add_f32_e32 v1, v26, v1
	v_cndmask_b32_e32 v18, v221, v228, vcc
	v_lshlrev_b32_e32 v18, 2, v18
	v_mov_b32_e32 v18, v1
	s_nop 1
	v_permlane32_swap_b32_e32 v18, v1
	s_and_saveexec_b64 s[12:13], s[4:5]
	s_cbranch_execz .LBB0_833
	v_lshl_add_u64 v[20:21], v[120:121], 2, s[10:11]
	s_waitcnt lgkmcnt(0)
	v_add_f32_e32 v1, v1, v18
	global_atomic_add_f32 v[20:21], v1, off offset:128

.LBB0_843:
	v_cmp_lt_i32_e32 vcc, v227, v222
	s_nop 1
	v_cndmask_b32_e32 v1, v221, v227, vcc
	v_lshlrev_b32_e32 v1, 2, v1
	v_mov_b32_e32 v1, v10
	s_nop 1
	v_permlane16_swap_b32_e32 v1, v10
	v_cmp_lt_i32_e32 vcc, v228, v222
	s_waitcnt lgkmcnt(0)
	v_add_f32_e32 v1, v10, v1
	v_cndmask_b32_e32 v2, v221, v228, vcc
	v_lshlrev_b32_e32 v2, 2, v2
	v_mov_b32_e32 v2, v1
	s_nop 1
	v_permlane32_swap_b32_e32 v2, v1
	s_and_saveexec_b64 s[6:7], s[4:5]
	s_cbranch_execz .LBB0_845
	v_lshl_add_u64 v[4:5], v[120:121], 2, s[10:11]
	s_waitcnt lgkmcnt(0)
	v_add_f32_e32 v1, v1, v2
	global_atomic_add_f32 v[4:5], v1, off offset:192
